# dv256: K-fragment LDS reads prefetched one MFMA pair ahead (double-buffered fragment registers) + counted lgkmcnt waits in P.V
# speedup vs baseline: 1.0140x; 1.0076x over previous
; #define LAS __attribute__((address_space(3)))
; __device__ __forceinline__ void attn_pass_dv256(const bf16_t* __restrict__ Qb, const bf16_t* __restrict__ Kh, const bf16_t* __restrict__ Vh, int qpos0,
;                                                 LAS unsigned char* lds, f32x16 (&o)[8], float& l_out, int wave_) {
;     ...
;     { const LAS unsigned char* Ks = K_lds + sl * SHM_K; p0 = f32x16{}; p1 = f32x16{};
; #pragma unroll
;       for (int d0 = 0; d0 < 8; ++d0) { const int cb = (d0 * 16 + hi * 8) * 2;
;         const bf16x8 b0 = *(const LAS bf16x8*)(Ks + KSWZ(r32, cb)), b1 = *(const LAS bf16x8*)(Ks + KSWZ(32 + r32, cb));
;         const bf16x8 q = d0 < 4 ? qr[d0 & 3] : *(const LAS bf16x8*)(qf + ((d0 - 4) * 64 + lane) * 16);
;         p0 = __builtin_amdgcn_mfma_f32_32x32x16_bf16(b0, q, p0, 0, 0, 0); p1 = __builtin_amdgcn_mfma_f32_32x32x16_bf16(b1, q, p1, 0, 0, 0); } }
.LBB0_374:
	s_and_b32 s47, s45, 1
	s_lshl_b32 s46, s47, 14
	v_add_u32_e32 v182, s46, v237
	v_add_u32_e32 v132, v182, v239
	ds_read_b128 v[128:131], v132
	ds_read_b128 v[144:147], v132 offset:8192
	v_add_u32_e32 v183, v182, v240
	ds_read_b128 v[178:181], v183
	ds_read_b128 v[192:195], v183 offset:8192
	v_add_u32_e32 v183, v182, v241
	ds_read_b128 v[200:203], v183
	ds_read_b128 v[204:207], v183 offset:8192
	s_add_i32 s16, s30, s37
	s_add_i32 s12, s16, 0xffffff61
	s_mov_b64 s[24:25], -1
	s_cmp_gt_u32 s12, 0xfffffea2
	s_waitcnt lgkmcnt(5)
	v_mfma_f32_32x32x16_bf16 v[128:143], v[128:131], v[160:163], 0
	s_waitcnt lgkmcnt(4)
	v_mfma_f32_32x32x16_bf16 v[144:159], v[144:147], v[160:163], 0
	s_waitcnt lgkmcnt(3)
	v_mfma_f32_32x32x16_bf16 v[128:143], v[178:181], v[168:171], v[128:143]
	s_waitcnt lgkmcnt(2)
	v_mfma_f32_32x32x16_bf16 v[144:159], v[192:195], v[168:171], v[144:159]
	v_add_u32_e32 v183, v182, v242
	ds_read_b128 v[178:181], v183
	ds_read_b128 v[192:195], v183 offset:8192
	s_waitcnt lgkmcnt(3)
	v_mfma_f32_32x32x16_bf16 v[128:143], v[200:203], v[172:175], v[128:143]
	s_waitcnt lgkmcnt(2)
	v_mfma_f32_32x32x16_bf16 v[144:159], v[204:207], v[172:175], v[144:159]
	v_add_u32_e32 v183, v182, v243
	ds_read_b128 v[200:203], v183
	ds_read_b128 v[204:207], v183 offset:8192
	ds_read_b128 v[208:211], v234
	s_waitcnt lgkmcnt(4)
	v_mfma_f32_32x32x16_bf16 v[128:143], v[178:181], v[164:167], v[128:143]
	s_waitcnt lgkmcnt(3)
	v_mfma_f32_32x32x16_bf16 v[144:159], v[192:195], v[164:167], v[144:159]
	v_add_u32_e32 v183, v182, v244
	ds_read_b128 v[178:181], v183
	ds_read_b128 v[192:195], v183 offset:8192
	ds_read_b128 v[196:199], v234 offset:1024
	s_waitcnt lgkmcnt(3)
	v_mfma_f32_32x32x16_bf16 v[128:143], v[200:203], v[208:211], v[128:143]
	v_mfma_f32_32x32x16_bf16 v[144:159], v[204:207], v[208:211], v[144:159]
	v_add_u32_e32 v183, v182, v245
	ds_read_b128 v[200:203], v183
	ds_read_b128 v[204:207], v183 offset:8192
	ds_read_b128 v[208:211], v234 offset:2048
	s_waitcnt lgkmcnt(3)
	v_mfma_f32_32x32x16_bf16 v[128:143], v[178:181], v[196:199], v[128:143]
	v_mfma_f32_32x32x16_bf16 v[144:159], v[192:195], v[196:199], v[144:159]
	v_add_u32_e32 v182, v182, v246
	ds_read_b128 v[178:181], v182
	ds_read_b128 v[192:195], v182 offset:8192
	ds_read_b128 v[196:199], v234 offset:3072
	s_waitcnt lgkmcnt(3)
	v_mfma_f32_32x32x16_bf16 v[128:143], v[200:203], v[208:211], v[128:143]
	v_mfma_f32_32x32x16_bf16 v[144:159], v[204:207], v[208:211], v[144:159]
	s_waitcnt lgkmcnt(0)
	v_mfma_f32_32x32x16_bf16 v[128:143], v[178:181], v[196:199], v[128:143]
	v_mfma_f32_32x32x16_bf16 v[144:159], v[192:195], v[196:199], v[144:159]
	s_cbranch_scc0 .LBB0_376
; #define LAS __attribute__((address_space(3)))
; __device__ __forceinline__ int crow(int r, int hi) { return (r & 3) + 8 * (r >> 2) + 4 * hi; }
; __device__ __forceinline__ void partialSM(f32x16& p0, f32x16& p1, float& m_reg, float& mn, float& alpha, float cadd) {
;   float pmax = p0[0];
; #pragma unroll
;   for (int r = 1; r < 16; ++r) pmax = fmaxf(pmax, p0[r]);
; #pragma unroll
;   for (int r = 0; r < 16; ++r) pmax = fmaxf(pmax, p1[r]);
;   { auto rr = __builtin_amdgcn_permlane32_swap(__float_as_uint(pmax), __float_as_uint(pmax), false, false);
;     pmax = fmaxf(__uint_as_float(rr[0]), __uint_as_float(rr[1])); }
;   pmax += cadd;
;   if (__builtin_expect(__all(pmax - m_reg <= THRL), 1)) { mn = m_reg; alpha = 1.f; }
; __device__ __forceinline__ void add_bias(f32x16& p0, f32x16& p1, const LAS float* tbl, int kq, int hi) {
; #pragma unroll
;   for (int r = 0; r < 16; ++r) { const int rel = kq + crow(r, hi);
;     p0[r] += tbl[min(max(rel, -128), 128) + 128]; p1[r] += tbl[min(max(rel + 32, -128), 128) + 128]; }
; }
; __device__ __forceinline__ void attn_pass_dv256(const bf16_t* __restrict__ Qb, const bf16_t* __restrict__ Kh, const bf16_t* __restrict__ Vh, int qpos0,
;                                                 LAS unsigned char* lds, f32x16 (&o)[8], float& l_out, int wave_) {
;     ...
;     { const int dd = j * KVBLK - qw0;
;       if (dd <= -191 || dd >= 159) { cadd = (dd < 0) ? tbl[0] : tbl[256]; partialSM(p0, p1, m_reg, mn, al, cadd); }
;       else { add_bias(p0, p1, tbl, j * KVBLK - qme, hi); partialSM(p0, p1, m_reg, mn, al, 0.f); } }
	v_add_u32_e32 v190, s37, v248
	v_add_u32_e32 v182, 2, v190
	s_add_i32 s12, 0, 0x18800
	v_med3_i32 v183, v182, s50, v228
	v_med3_i32 v182, v182, s51, v229
	v_lshl_add_u32 v194, v182, 2, s12
	v_add_u32_e32 v182, 3, v190
	v_med3_i32 v178, v190, s50, v228
	v_med3_i32 v179, v190, s51, v229
	v_add_u32_e32 v180, 1, v190
	v_lshl_add_u32 v191, v183, 2, s12
	v_med3_i32 v183, v182, s50, v228
	v_med3_i32 v182, v182, s51, v229
	v_lshl_add_u32 v178, v178, 2, s12
	v_lshl_add_u32 v179, v179, 2, s12
	v_med3_i32 v181, v180, s50, v228
	v_med3_i32 v180, v180, s51, v229
	v_lshl_add_u32 v193, v183, 2, s12
	v_lshl_add_u32 v195, v182, 2, s12
	v_lshl_add_u32 v181, v181, 2, s12
	v_lshl_add_u32 v180, v180, 2, s12
	ds_read_b32 v178, v178 offset:512
	ds_read_b32 v182, v179 offset:640
	ds_read_b32 v179, v181 offset:512
	ds_read_b32 v183, v180 offset:640
	ds_read_b32 v192, v191 offset:512
	ds_read_b32 v193, v193 offset:512
	ds_read_b32 v195, v195 offset:640
	ds_read_b32 v194, v194 offset:640
	s_waitcnt lgkmcnt(5)
	v_pk_add_f32 v[180:181], v[128:129], v[178:179]
	s_waitcnt lgkmcnt(4)
	v_pk_add_f32 v[178:179], v[144:145], v[182:183]
	s_waitcnt lgkmcnt(2)
	v_pk_add_f32 v[182:183], v[130:131], v[192:193]
	v_add_u32_e32 v193, 9, v190
	v_med3_i32 v196, v193, s50, v228
	v_lshl_add_u32 v197, v196, 2, s12
	v_add_u32_e32 v196, 10, v190
	v_med3_i32 v198, v196, s50, v228
	v_med3_i32 v196, v196, s51, v229
	v_add_u32_e32 v191, 8, v190
	v_lshl_add_u32 v199, v196, 2, s12
	v_add_u32_e32 v196, 11, v190
	v_med3_i32 v192, v191, s50, v228
	v_med3_i32 v200, v196, s50, v228
	v_med3_i32 v196, v196, s51, v229
	v_lshl_add_u32 v192, v192, 2, s12
	v_med3_i32 v191, v191, s51, v229
	v_med3_i32 v193, v193, s51, v229
	v_lshl_add_u32 v203, v200, 2, s12
	v_lshl_add_u32 v205, v196, 2, s12
	v_lshl_add_u32 v191, v191, 2, s12
	v_lshl_add_u32 v193, v193, 2, s12
	v_lshl_add_u32 v198, v198, 2, s12
	ds_read_b32 v196, v192 offset:512
	ds_read_b32 v200, v191 offset:640
	ds_read_b32 v197, v197 offset:512
	ds_read_b32 v201, v193 offset:640
	ds_read_b32 v202, v198 offset:512
	ds_read_b32 v204, v199 offset:640
	ds_read_b32 v203, v203 offset:512
	ds_read_b32 v205, v205 offset:640
	s_waitcnt lgkmcnt(8)
	v_pk_add_f32 v[192:193], v[146:147], v[194:195]
	s_waitcnt lgkmcnt(4)
	v_pk_add_f32 v[194:195], v[148:149], v[200:201]
	v_pk_add_f32 v[198:199], v[132:133], v[196:197]
	s_waitcnt lgkmcnt(1)
	v_pk_add_f32 v[200:201], v[134:135], v[202:203]
	v_add_u32_e32 v203, 17, v190
	s_waitcnt lgkmcnt(0)
	v_pk_add_f32 v[196:197], v[150:151], v[204:205]
	v_med3_i32 v204, v203, s50, v228
	v_med3_i32 v203, v203, s51, v229
	v_lshl_add_u32 v205, v203, 2, s12
	v_add_u32_e32 v203, 18, v190
	v_med3_i32 v206, v203, s50, v228
	v_med3_i32 v203, v203, s51, v229
	v_add_u32_e32 v191, 16, v190
	v_lshl_add_u32 v210, v203, 2, s12
	v_add_u32_e32 v203, 19, v190
	v_med3_i32 v202, v191, s50, v228
	v_lshl_add_u32 v208, v206, 2, s12
	v_med3_i32 v206, v203, s50, v228
	v_med3_i32 v203, v203, s51, v229
	v_lshl_add_u32 v202, v202, 2, s12
	v_med3_i32 v191, v191, s51, v229
	v_lshl_add_u32 v209, v206, 2, s12
	v_lshl_add_u32 v211, v203, 2, s12
	v_lshl_add_u32 v191, v191, 2, s12
	v_lshl_add_u32 v204, v204, 2, s12
	ds_read_b32 v202, v202 offset:512
	ds_read_b32 v206, v191 offset:640
	ds_read_b32 v203, v204 offset:512
	ds_read_b32 v207, v205 offset:640
	ds_read_b32 v208, v208 offset:512
	ds_read_b32 v209, v209 offset:512
	ds_read_b32 v211, v211 offset:640
	ds_read_b32 v210, v210 offset:640
	s_waitcnt lgkmcnt(5)
	v_pk_add_f32 v[204:205], v[136:137], v[202:203]
	s_waitcnt lgkmcnt(4)
	v_pk_add_f32 v[202:203], v[152:153], v[206:207]
	s_waitcnt lgkmcnt(2)
	v_pk_add_f32 v[206:207], v[138:139], v[208:209]
	v_add_u32_e32 v209, 25, v190
	v_med3_i32 v212, v209, s50, v228
	v_lshl_add_u32 v213, v212, 2, s12
	v_add_u32_e32 v212, 26, v190
	v_add_u32_e32 v191, 24, v190
	v_med3_i32 v214, v212, s50, v228
	v_med3_i32 v212, v212, s51, v229
	v_add_u32_e32 v190, 27, v190
	v_med3_i32 v208, v191, s50, v228
	v_med3_i32 v191, v191, s51, v229
	v_lshl_add_u32 v215, v212, 2, s12
	v_med3_i32 v212, v190, s50, v228
	v_med3_i32 v190, v190, s51, v229
	v_lshl_add_u32 v208, v208, 2, s12
	v_lshl_add_u32 v191, v191, 2, s12
	v_med3_i32 v209, v209, s51, v229
	v_lshl_add_u32 v223, v190, 2, s12
	v_lshl_add_u32 v209, v209, 2, s12
	v_lshl_add_u32 v214, v214, 2, s12
	v_lshl_add_u32 v221, v212, 2, s12
	ds_read_b32 v212, v208 offset:512
	ds_read_b32 v216, v191 offset:640
	ds_read_b32 v213, v213 offset:512
	ds_read_b32 v217, v209 offset:640
	ds_read_b32 v190, v214 offset:512
	ds_read_b32 v222, v215 offset:640
	ds_read_b32 v191, v221 offset:512
	ds_read_b32 v223, v223 offset:640
	s_waitcnt lgkmcnt(8)
	v_pk_add_f32 v[208:209], v[154:155], v[210:211]
	s_waitcnt lgkmcnt(4)
	v_pk_add_f32 v[210:211], v[156:157], v[216:217]
	v_pk_add_f32 v[214:215], v[140:141], v[212:213]
	s_waitcnt lgkmcnt(1)
	v_pk_add_f32 v[216:217], v[142:143], v[190:191]
	v_max_f32_e32 v190, v180, v181
	v_max3_f32 v190, v190, v182, v183
	v_max3_f32 v190, v190, v198, v199
	v_max3_f32 v190, v190, v200, v201
	v_max3_f32 v190, v190, v204, v205
	v_max3_f32 v190, v190, v206, v207
	v_max3_f32 v190, v190, v214, v215
	v_max3_f32 v190, v190, v216, v217
	v_max3_f32 v190, v190, v178, v179
	v_max3_f32 v190, v190, v192, v193
	v_max3_f32 v190, v190, v194, v195
	v_max3_f32 v190, v190, v196, v197
	v_max3_f32 v190, v190, v202, v203
	v_max3_f32 v190, v190, v208, v209
	s_waitcnt lgkmcnt(0)
	v_pk_add_f32 v[212:213], v[158:159], v[222:223]
	v_max3_f32 v190, v190, v210, v211
	v_max3_f32 v190, v190, v212, v213
	v_mov_b32_e32 v191, v190
	s_nop 1
	v_permlane32_swap_b32_e32 v190, v191
	v_max_f32_e32 v191, v191, v191
	v_max_f32_e32 v190, v190, v190
	v_max_f32_e32 v190, v190, v191
	v_add_f32_e32 v221, 0, v190
	v_sub_f32_e32 v190, v221, v249
	v_cmp_ge_f32_e32 vcc, s94, v190
	s_cmp_eq_u64 vcc, exec
	s_mov_b64 s[24:25], 0
	s_cselect_b64 s[12:13], -1, 0

; #define SBAR() __builtin_amdgcn_sched_barrier(0)
; template <int OFF> __device__ __forceinline__ s16x4 tr_read(unsigned vb) { s16x4 r; asm volatile("ds_read_b64_tr_b16 %0, %1 offset:%2" : "=&v"(r) : "v"(vb), "i"(OFF) : "memory"); return r; }
; template <int D0> __device__ __forceinline__ void pv_one(f32x16& od, unsigned vb, bf16x8 pa0, bf16x8 pa1, bf16x8 pa2, bf16x8 pa3) {
;   const s16x4 l0 = tr_read<v_rd_off(D0, 0, 0)>(vb), h0 = tr_read<v_rd_off(D0, 0, 1)>(vb), l1 = tr_read<v_rd_off(D0, 1, 0)>(vb), h1 = tr_read<v_rd_off(D0, 1, 1)>(vb);
;   const s16x4 l2 = tr_read<v_rd_off(D0, 2, 0)>(vb), h2 = tr_read<v_rd_off(D0, 2, 1)>(vb), l3 = tr_read<v_rd_off(D0, 3, 0)>(vb), h3 = tr_read<v_rd_off(D0, 3, 1)>(vb);
;   asm volatile("s_waitcnt lgkmcnt(0)" ::: "memory"); SBAR();
;     ...
;   od = __builtin_amdgcn_mfma_f32_32x32x16_bf16(pa0, PK(l0, h0), od, 0, 0, 0);
;   od = __builtin_amdgcn_mfma_f32_32x32x16_bf16(pa1, PK(l1, h1), od, 0, 0, 0);
;   od = __builtin_amdgcn_mfma_f32_32x32x16_bf16(pa2, PK(l2, h2), od, 0, 0, 0);
;   od = __builtin_amdgcn_mfma_f32_32x32x16_bf16(pa3, PK(l3, h3), od, 0, 0, 0);
;     ...
; }
; __device__ __forceinline__ void finishSM(f32x16& p0, f32x16& p1, float alpha, float& l_reg, bf16x8& pa0, bf16x8& pa1, bf16x8& pa2, bf16x8& pa3) {
; #pragma unroll
;   for (int r = 0; r < 16; ++r) p1[r] = __builtin_amdgcn_exp2f(p1[r]);
;   float ps = 0;
; #pragma unroll
;   for (int r = 0; r < 16; ++r) ps += p0[r];
; #pragma unroll
;   for (int r = 0; r < 16; ++r) ps += p1[r];
;   { auto rr = __builtin_amdgcn_permlane32_swap(__float_as_uint(ps), __float_as_uint(ps), false, false);
;     ps = __uint_as_float(rr[0]) + __uint_as_float(rr[1]); }
;   l_reg = l_reg * alpha + ps;
;     ...
;   PK4(p0, 0, pa0); PK4(p0, 8, pa1); PK4(p1, 0, pa2); PK4(p1, 8, pa3);
;     ...
; }
.Ljoin_p1:
	v_exp_f32_e32 v132, v132
	v_exp_f32_e32 v133, v133
	v_exp_f32_e32 v181, v128
	v_add_f32_e32 v128, 0, v129
	v_exp_f32_e32 v134, v134
	v_add_f32_e32 v128, v130, v128
	v_exp_f32_e32 v135, v135
	v_add_f32_e32 v128, v131, v128
	v_exp_f32_e32 v136, v136
	v_add_f32_e32 v128, v132, v128
	v_exp_f32_e32 v137, v137
	v_add_f32_e32 v128, v133, v128
	v_exp_f32_e32 v138, v138
	v_add_f32_e32 v128, v134, v128
	v_exp_f32_e32 v139, v139
	v_add_f32_e32 v128, v135, v128
	v_exp_f32_e32 v140, v140
	v_add_f32_e32 v128, v136, v128
	v_exp_f32_e32 v141, v141
	v_add_f32_e32 v128, v137, v128
	v_exp_f32_e32 v142, v142
	v_add_f32_e32 v128, v138, v128
	v_exp_f32_e32 v143, v143
	v_add_f32_e32 v128, v139, v128
	v_exp_f32_e32 v179, v145
	v_add_f32_e32 v128, v140, v128
	v_exp_f32_e32 v180, v146
	v_add_f32_e32 v128, v141, v128
	v_exp_f32_e32 v147, v147
	v_add_f32_e32 v128, v142, v128
	v_exp_f32_e32 v148, v148
	v_add_f32_e32 v128, v143, v128
	v_exp_f32_e32 v149, v149
	v_add_f32_e32 v128, v179, v128
	v_exp_f32_e32 v150, v150
	v_add_f32_e32 v128, v180, v128
	v_exp_f32_e32 v151, v151
	v_add_f32_e32 v128, v147, v128
	v_exp_f32_e32 v152, v152
	v_add_f32_e32 v128, v148, v128
	v_exp_f32_e32 v153, v153
	v_add_f32_e32 v128, v149, v128
	v_exp_f32_e32 v154, v154
	v_add_f32_e32 v128, v150, v128
	v_exp_f32_e32 v155, v155
	v_add_f32_e32 v128, v151, v128
	v_exp_f32_e32 v156, v156
	v_add_f32_e32 v128, v152, v128
	v_exp_f32_e32 v157, v157
	v_add_f32_e32 v128, v153, v128
	v_exp_f32_e32 v158, v158
	v_add_f32_e32 v128, v154, v128
	v_exp_f32_e32 v159, v159
	v_add_f32_e32 v128, v155, v128
	v_exp_f32_e32 v178, v178
	v_add_f32_e32 v128, v156, v128
	v_add_f32_e32 v128, v157, v128
	v_add_f32_e32 v128, v158, v128
	v_add_f32_e32 v128, v159, v128
	v_add_f32_e32 v128, v178, v128
	v_add_f32_e32 v145, v181, v128
	v_mov_b32_e32 v146, v145
	s_nop 1
	v_permlane32_swap_b32_e32 v145, v146
	v_cvt_pk_bf16_f32 v128, v129, v130
	v_cvt_pk_bf16_f32 v129, v131, v132
	v_cvt_pk_bf16_f32 v130, v133, v134
	v_cvt_pk_bf16_f32 v131, v135, v136
	v_cvt_pk_bf16_f32 v132, v137, v138
	v_cvt_pk_bf16_f32 v133, v139, v140
	v_cvt_pk_bf16_f32 v134, v141, v142
	v_cvt_pk_bf16_f32 v135, v143, v179
	v_cvt_pk_bf16_f32 v136, v180, v147
	v_cvt_pk_bf16_f32 v137, v148, v149
	v_cvt_pk_bf16_f32 v138, v150, v151
	v_cvt_pk_bf16_f32 v139, v152, v153
	v_cvt_pk_bf16_f32 v140, v154, v155
	v_cvt_pk_bf16_f32 v141, v156, v157
	v_cvt_pk_bf16_f32 v142, v158, v159
	v_cvt_pk_bf16_f32 v143, v178, v181
	v_permlane32_swap_b32_e32 v128, v130
	v_permlane32_swap_b32_e32 v129, v131
	v_permlane32_swap_b32_e32 v132, v134
	v_permlane32_swap_b32_e32 v133, v135
	v_permlane32_swap_b32_e32 v136, v138
	v_permlane32_swap_b32_e32 v137, v139
	v_permlane32_swap_b32_e32 v140, v142
	v_permlane32_swap_b32_e32 v141, v143
	s_lshl_b32 s12, s47, 15
	v_add_u32_e32 v147, s12, v247
	ds_read_b64_tr_b16 v[148:149], v147 offset:0
	ds_read_b64_tr_b16 v[150:151], v147 offset:0x800
	ds_read_b64_tr_b16 v[152:153], v147 offset:0x1000
	ds_read_b64_tr_b16 v[154:155], v147 offset:0x1800
	ds_read_b64_tr_b16 v[156:157], v147 offset:0x2000
	ds_read_b64_tr_b16 v[158:159], v147 offset:0x2800
	ds_read_b64_tr_b16 v[178:179], v147 offset:0x3000
	ds_read_b64_tr_b16 v[180:181], v147 offset:0x3800
	s_waitcnt lgkmcnt(6)
	s_nop 0
	v_mfma_f32_32x32x16_bf16 v[96:111], v[128:131], v[148:151], v[96:111]
	ds_read_b64_tr_b16 v[148:149], v147 offset:0x200
	ds_read_b64_tr_b16 v[150:151], v147 offset:0xa00
	s_waitcnt lgkmcnt(6)
	v_mfma_f32_32x32x16_bf16 v[96:111], v[132:135], v[152:155], v[96:111]
	ds_read_b64_tr_b16 v[152:153], v147 offset:0x1200
	ds_read_b64_tr_b16 v[154:155], v147 offset:0x1a00
	s_waitcnt lgkmcnt(6)
	v_mfma_f32_32x32x16_bf16 v[96:111], v[136:139], v[156:159], v[96:111]
	ds_read_b64_tr_b16 v[156:157], v147 offset:0x2200
	ds_read_b64_tr_b16 v[158:159], v147 offset:0x2a00
	s_waitcnt lgkmcnt(6)
	v_mfma_f32_32x32x16_bf16 v[96:111], v[140:143], v[178:181], v[96:111]
	ds_read_b64_tr_b16 v[178:179], v147 offset:0x3200
	ds_read_b64_tr_b16 v[180:181], v147 offset:0x3a00
	s_waitcnt lgkmcnt(6)
	v_mfma_f32_32x32x16_bf16 v[112:127], v[128:131], v[148:151], v[112:127]
	ds_read_b64_tr_b16 v[148:149], v147 offset:0x400
	ds_read_b64_tr_b16 v[150:151], v147 offset:0xc00
	s_waitcnt lgkmcnt(6)
	v_mfma_f32_32x32x16_bf16 v[112:127], v[132:135], v[152:155], v[112:127]
	ds_read_b64_tr_b16 v[152:153], v147 offset:0x1400
	ds_read_b64_tr_b16 v[154:155], v147 offset:0x1c00
	s_waitcnt lgkmcnt(6)
	v_mfma_f32_32x32x16_bf16 v[112:127], v[136:139], v[156:159], v[112:127]
	ds_read_b64_tr_b16 v[156:157], v147 offset:0x2400
	ds_read_b64_tr_b16 v[158:159], v147 offset:0x2c00
	s_waitcnt lgkmcnt(6)
	v_mfma_f32_32x32x16_bf16 v[112:127], v[140:143], v[178:181], v[112:127]
	ds_read_b64_tr_b16 v[178:179], v147 offset:0x3400
	ds_read_b64_tr_b16 v[180:181], v147 offset:0x3c00
	s_waitcnt lgkmcnt(6)
	v_mfma_f32_32x32x16_bf16 v[64:79], v[128:131], v[148:151], v[64:79]
	ds_read_b64_tr_b16 v[148:149], v147 offset:0x600
	ds_read_b64_tr_b16 v[150:151], v147 offset:0xe00
	s_waitcnt lgkmcnt(6)
; #define BARL() asm volatile("s_waitcnt lgkmcnt(0)\n\ts_barrier" ::: "memory")
; #define BARL() asm volatile("s_waitcnt lgkmcnt(0)\n\ts_barrier" ::: "memory")
; __device__ __forceinline__ void attn_pass_dv256(const bf16_t* __restrict__ Qb, const bf16_t* __restrict__ Kh, const bf16_t* __restrict__ Vh, int qpos0,
;                                                 LAS unsigned char* lds, f32x16 (&o)[8], float& l_out, int wave_) {
;     ...
;     pv_one<0>(o[0], vbs, pa0, pa1, pa2, pa3); pv_one<1>(o[1], vbs, pa0, pa1, pa2, pa3); pv_one<2>(o[2], vbs, pa0, pa1, pa2, pa3); pv_one<3>(o[3], vbs, pa0, pa1, pa2, pa3);
;     pv_one<0>(o[4], vbs + 16384, pa0, pa1, pa2, pa3); pv_one<1>(o[5], vbs + 16384, pa0, pa1, pa2, pa3); pv_one<2>(o[6], vbs + 16384, pa0, pa1, pa2, pa3); pv_one<3>(o[7], vbs + 16384, pa0, pa1, pa2, pa3);
;     asm volatile("s_waitcnt vmcnt(0)" ::: "memory"); BARL();
;     if (j + 2 < NT) DMA_KV(j + 2, sl);
	v_mfma_f32_32x32x16_bf16 v[64:79], v[132:135], v[152:155], v[64:79]
	ds_read_b64_tr_b16 v[152:153], v147 offset:0x1600
	ds_read_b64_tr_b16 v[154:155], v147 offset:0x1e00
	s_waitcnt lgkmcnt(6)
	v_mfma_f32_32x32x16_bf16 v[64:79], v[136:139], v[156:159], v[64:79]
	ds_read_b64_tr_b16 v[156:157], v147 offset:0x2600
	ds_read_b64_tr_b16 v[158:159], v147 offset:0x2e00
	s_waitcnt lgkmcnt(6)
	v_mfma_f32_32x32x16_bf16 v[64:79], v[140:143], v[178:181], v[64:79]
	ds_read_b64_tr_b16 v[178:179], v147 offset:0x3600
	ds_read_b64_tr_b16 v[180:181], v147 offset:0x3e00
	s_waitcnt lgkmcnt(6)
	v_mfma_f32_32x32x16_bf16 v[80:95], v[128:131], v[148:151], v[80:95]
	v_add_u32_e32 v147, 0x4000, v147
	ds_read_b64_tr_b16 v[148:149], v147 offset:0
	ds_read_b64_tr_b16 v[150:151], v147 offset:0x800
	s_waitcnt lgkmcnt(6)
	v_mfma_f32_32x32x16_bf16 v[80:95], v[132:135], v[152:155], v[80:95]
	ds_read_b64_tr_b16 v[152:153], v147 offset:0x1000
	ds_read_b64_tr_b16 v[154:155], v147 offset:0x1800
	s_waitcnt lgkmcnt(6)
	v_mfma_f32_32x32x16_bf16 v[80:95], v[136:139], v[156:159], v[80:95]
	ds_read_b64_tr_b16 v[156:157], v147 offset:0x2000
	ds_read_b64_tr_b16 v[158:159], v147 offset:0x2800
	s_waitcnt lgkmcnt(6)
	v_mfma_f32_32x32x16_bf16 v[80:95], v[140:143], v[178:181], v[80:95]
	ds_read_b64_tr_b16 v[178:179], v147 offset:0x3000
	ds_read_b64_tr_b16 v[180:181], v147 offset:0x3800
	s_waitcnt lgkmcnt(6)
	v_mfma_f32_32x32x16_bf16 v[32:47], v[128:131], v[148:151], v[32:47]
	ds_read_b64_tr_b16 v[148:149], v147 offset:0x200
	ds_read_b64_tr_b16 v[150:151], v147 offset:0xa00
	s_waitcnt lgkmcnt(6)
	v_mfma_f32_32x32x16_bf16 v[32:47], v[132:135], v[152:155], v[32:47]
	ds_read_b64_tr_b16 v[152:153], v147 offset:0x1200
	ds_read_b64_tr_b16 v[154:155], v147 offset:0x1a00
	s_waitcnt lgkmcnt(6)
	v_mfma_f32_32x32x16_bf16 v[32:47], v[136:139], v[156:159], v[32:47]
	ds_read_b64_tr_b16 v[156:157], v147 offset:0x2200
	ds_read_b64_tr_b16 v[158:159], v147 offset:0x2a00
	s_waitcnt lgkmcnt(6)
	v_mfma_f32_32x32x16_bf16 v[32:47], v[140:143], v[178:181], v[32:47]
	ds_read_b64_tr_b16 v[178:179], v147 offset:0x3200
	ds_read_b64_tr_b16 v[180:181], v147 offset:0x3a00
	s_waitcnt lgkmcnt(6)
	v_mfma_f32_32x32x16_bf16 v[48:63], v[128:131], v[148:151], v[48:63]
	ds_read_b64_tr_b16 v[148:149], v147 offset:0x400
	ds_read_b64_tr_b16 v[150:151], v147 offset:0xc00
	s_waitcnt lgkmcnt(6)
	v_mfma_f32_32x32x16_bf16 v[48:63], v[132:135], v[152:155], v[48:63]
	ds_read_b64_tr_b16 v[152:153], v147 offset:0x1400
	ds_read_b64_tr_b16 v[154:155], v147 offset:0x1c00
	s_waitcnt lgkmcnt(6)
	v_mfma_f32_32x32x16_bf16 v[48:63], v[136:139], v[156:159], v[48:63]
	ds_read_b64_tr_b16 v[156:157], v147 offset:0x2400
	ds_read_b64_tr_b16 v[158:159], v147 offset:0x2c00
	s_waitcnt lgkmcnt(6)
	v_mfma_f32_32x32x16_bf16 v[48:63], v[140:143], v[178:181], v[48:63]
	ds_read_b64_tr_b16 v[178:179], v147 offset:0x3400
	ds_read_b64_tr_b16 v[180:181], v147 offset:0x3c00
	s_waitcnt lgkmcnt(6)
	v_mfma_f32_32x32x16_bf16 v[16:31], v[128:131], v[148:151], v[16:31]
	ds_read_b64_tr_b16 v[148:149], v147 offset:0x600
	ds_read_b64_tr_b16 v[150:151], v147 offset:0xe00
	s_waitcnt lgkmcnt(6)
	v_mfma_f32_32x32x16_bf16 v[16:31], v[132:135], v[152:155], v[16:31]
	ds_read_b64_tr_b16 v[152:153], v147 offset:0x1600
	ds_read_b64_tr_b16 v[154:155], v147 offset:0x1e00
	s_waitcnt lgkmcnt(6)
	v_mfma_f32_32x32x16_bf16 v[16:31], v[136:139], v[156:159], v[16:31]
	ds_read_b64_tr_b16 v[156:157], v147 offset:0x2600
	ds_read_b64_tr_b16 v[158:159], v147 offset:0x2e00
	s_waitcnt lgkmcnt(6)
	v_mfma_f32_32x32x16_bf16 v[16:31], v[140:143], v[178:181], v[16:31]
	ds_read_b64_tr_b16 v[178:179], v147 offset:0x3600
	ds_read_b64_tr_b16 v[180:181], v147 offset:0x3e00
	s_waitcnt lgkmcnt(6)
	v_mfma_f32_32x32x16_bf16 v[0:15], v[128:131], v[148:151], v[0:15]
	s_waitcnt vmcnt(0)
	s_waitcnt lgkmcnt(0)
	s_barrier
	s_cmp_gt_u32 s45, 61
	v_mfma_f32_32x32x16_bf16 v[0:15], v[132:135], v[152:155], v[0:15]
	v_mfma_f32_32x32x16_bf16 v[0:15], v[136:139], v[156:159], v[0:15]
	v_mfma_f32_32x32x16_bf16 v[0:15], v[140:143], v[178:181], v[0:15]
	s_cbranch_scc1 .LBB0_384
	s_add_u32 s13, s40, s27
	s_addc_u32 s47, s41, 0
	s_add_u32 s16, s13, 0x21080000
	s_addc_u32 s17, s47, 0
	s_add_u32 s48, s43, s27
	s_addc_u32 s49, s44, 0
	s_add_u32 s24, s48, 0x29080000
	s_addc_u32 s25, s49, 0
	s_add_i32 s46, s46, 0
	s_add_i32 s46, s46, 0x10000
	s_add_i32 s52, s46, s68
	s_mov_b32 m0, s52
	s_nop 0
	global_load_lds_dwordx4 v235, s[16:17]
	s_add_u32 s16, s13, 0x210a0000
	s_addc_u32 s17, s47, 0
	s_add_i32 s46, s46, s0
	s_mov_b32 m0, s46
	s_nop 0
	global_load_lds_dwordx4 v235, s[16:17]
	s_add_i32 s16, s12, 0
	s_add_i32 s12, s16, s68
	s_mov_b32 m0, s12
	s_nop 0
	global_load_lds_dwordx4 v236, s[24:25]
	s_add_u32 s12, s48, 0x290a0000
	s_addc_u32 s13, s49, 0
	s_add_i32 s17, s16, s0
	s_mov_b32 m0, s17
	s_nop 0
	global_load_lds_dwordx4 v236, s[12:13]
	s_add_u32 s12, s48, 0x29080100
	s_addc_u32 s13, s49, 0
	s_addk_i32 s16, 0x4000
	s_add_i32 s17, s16, s68
	s_mov_b32 m0, s17
	s_nop 0
	global_load_lds_dwordx4 v236, s[12:13]
	s_add_u32 s12, s48, 0x290a0100
	s_addc_u32 s13, s49, 0
	s_add_i32 s16, s16, s0
	s_mov_b32 m0, s16
	s_nop 0
	global_load_lds_dwordx4 v236, s[12:13]

; #define LAS __attribute__((address_space(3)))
; __device__ __forceinline__ void attn_pass_dv256(const bf16_t* __restrict__ Qb, const bf16_t* __restrict__ Kh, const bf16_t* __restrict__ Vh, int qpos0,
;                                                 LAS unsigned char* lds, f32x16 (&o)[8], float& l_out, int wave_) {
;     ...
;     { const LAS unsigned char* Ks = K_lds + sl * SHM_K; p0 = f32x16{}; p1 = f32x16{};
; #pragma unroll
;       for (int d0 = 0; d0 < 8; ++d0) { const int cb = (d0 * 16 + hi * 8) * 2;
;         const bf16x8 b0 = *(const LAS bf16x8*)(Ks + KSWZ(r32, cb)), b1 = *(const LAS bf16x8*)(Ks + KSWZ(32 + r32, cb));
;         const bf16x8 q = d0 < 4 ? qr[d0 & 3] : *(const LAS bf16x8*)(qf + ((d0 - 4) * 64 + lane) * 16);
;         p0 = __builtin_amdgcn_mfma_f32_32x32x16_bf16(b0, q, p0, 0, 0, 0); p1 = __builtin_amdgcn_mfma_f32_32x32x16_bf16(b1, q, p1, 0, 0, 0); } }
.LBB0_389:
	s_and_b32 s19, s17, 1
	s_lshl_b32 s18, s19, 14
	v_add_u32_e32 v182, s18, v237
	v_add_u32_e32 v132, v182, v239
	ds_read_b128 v[128:131], v132
	ds_read_b128 v[144:147], v132 offset:8192
	v_add_u32_e32 v183, v182, v240
	ds_read_b128 v[178:181], v183
	ds_read_b128 v[192:195], v183 offset:8192
	v_add_u32_e32 v183, v182, v241
	ds_read_b128 v[200:203], v183
	ds_read_b128 v[204:207], v183 offset:8192
	s_add_i32 s24, s30, s16
	s_add_i32 s6, s24, 0xffffff61
	s_mov_b64 s[8:9], -1
	s_cmp_gt_u32 s6, 0xfffffea2
	s_waitcnt lgkmcnt(5)
	v_mfma_f32_32x32x16_bf16 v[128:143], v[128:131], v[160:163], 0
	s_waitcnt lgkmcnt(4)
	v_mfma_f32_32x32x16_bf16 v[144:159], v[144:147], v[160:163], 0
	s_waitcnt lgkmcnt(3)
	v_mfma_f32_32x32x16_bf16 v[128:143], v[178:181], v[164:167], v[128:143]
	s_waitcnt lgkmcnt(2)
	v_mfma_f32_32x32x16_bf16 v[144:159], v[192:195], v[164:167], v[144:159]
	v_add_u32_e32 v183, v182, v242
	ds_read_b128 v[178:181], v183
	ds_read_b128 v[192:195], v183 offset:8192
	s_waitcnt lgkmcnt(3)
	v_mfma_f32_32x32x16_bf16 v[128:143], v[200:203], v[168:171], v[128:143]
	s_waitcnt lgkmcnt(2)
	v_mfma_f32_32x32x16_bf16 v[144:159], v[204:207], v[168:171], v[144:159]
	v_add_u32_e32 v183, v182, v243
	ds_read_b128 v[200:203], v183
	ds_read_b128 v[204:207], v183 offset:8192
	ds_read_b128 v[208:211], v234
	s_waitcnt lgkmcnt(4)
	v_mfma_f32_32x32x16_bf16 v[128:143], v[178:181], v[172:175], v[128:143]
	s_waitcnt lgkmcnt(3)
	v_mfma_f32_32x32x16_bf16 v[144:159], v[192:195], v[172:175], v[144:159]
	v_add_u32_e32 v183, v182, v244
	ds_read_b128 v[178:181], v183
	ds_read_b128 v[192:195], v183 offset:8192
	ds_read_b128 v[196:199], v234 offset:1024
	s_waitcnt lgkmcnt(3)
	v_mfma_f32_32x32x16_bf16 v[128:143], v[200:203], v[208:211], v[128:143]
	v_mfma_f32_32x32x16_bf16 v[144:159], v[204:207], v[208:211], v[144:159]
	v_add_u32_e32 v183, v182, v245
	ds_read_b128 v[200:203], v183
	ds_read_b128 v[204:207], v183 offset:8192
	ds_read_b128 v[208:211], v234 offset:2048
	s_waitcnt lgkmcnt(3)
	v_mfma_f32_32x32x16_bf16 v[128:143], v[178:181], v[196:199], v[128:143]
	v_mfma_f32_32x32x16_bf16 v[144:159], v[192:195], v[196:199], v[144:159]
	v_add_u32_e32 v182, v182, v246
	ds_read_b128 v[178:181], v182
	ds_read_b128 v[192:195], v182 offset:8192
	ds_read_b128 v[196:199], v234 offset:3072
	s_waitcnt lgkmcnt(3)
	v_mfma_f32_32x32x16_bf16 v[128:143], v[200:203], v[208:211], v[128:143]
	v_mfma_f32_32x32x16_bf16 v[144:159], v[204:207], v[208:211], v[144:159]
	s_waitcnt lgkmcnt(0)
	v_mfma_f32_32x32x16_bf16 v[128:143], v[178:181], v[196:199], v[128:143]
	v_mfma_f32_32x32x16_bf16 v[144:159], v[192:195], v[196:199], v[144:159]
	s_cbranch_scc0 .LBB0_391
; #define LAS __attribute__((address_space(3)))
; __device__ __forceinline__ int crow(int r, int hi) { return (r & 3) + 8 * (r >> 2) + 4 * hi; }
; __device__ __forceinline__ void partialSM(f32x16& p0, f32x16& p1, float& m_reg, float& mn, float& alpha, float cadd) {
;   float pmax = p0[0];
; #pragma unroll
;   for (int r = 1; r < 16; ++r) pmax = fmaxf(pmax, p0[r]);
; #pragma unroll
;   for (int r = 0; r < 16; ++r) pmax = fmaxf(pmax, p1[r]);
;   { auto rr = __builtin_amdgcn_permlane32_swap(__float_as_uint(pmax), __float_as_uint(pmax), false, false);
;     pmax = fmaxf(__uint_as_float(rr[0]), __uint_as_float(rr[1])); }
;   pmax += cadd;
;   if (__builtin_expect(__all(pmax - m_reg <= THRL), 1)) { mn = m_reg; alpha = 1.f; }
; __device__ __forceinline__ void add_bias(f32x16& p0, f32x16& p1, const LAS float* tbl, int kq, int hi) {
; #pragma unroll
;   for (int r = 0; r < 16; ++r) { const int rel = kq + crow(r, hi);
;     p0[r] += tbl[min(max(rel, -128), 128) + 128]; p1[r] += tbl[min(max(rel + 32, -128), 128) + 128]; }
; }
; __device__ __forceinline__ void attn_pass_dv256(const bf16_t* __restrict__ Qb, const bf16_t* __restrict__ Kh, const bf16_t* __restrict__ Vh, int qpos0,
;                                                 LAS unsigned char* lds, f32x16 (&o)[8], float& l_out, int wave_) {
;     ...
;     { const int dd = j * KVBLK - qw0;
;       if (dd <= -191 || dd >= 159) { cadd = (dd < 0) ? tbl[0] : tbl[256]; partialSM(p0, p1, m_reg, mn, al, cadd); }
;       else { add_bias(p0, p1, tbl, j * KVBLK - qme, hi); partialSM(p0, p1, m_reg, mn, al, 0.f); } }
	v_add_u32_e32 v210, s16, v248
	v_add_u32_e32 v182, 2, v210
	s_add_i32 s6, 0, 0x18800
	v_med3_i32 v183, v182, s50, v228
	v_med3_i32 v182, v182, s51, v229
	v_lshl_add_u32 v192, v182, 2, s6
	v_add_u32_e32 v182, 3, v210
	v_med3_i32 v178, v210, s50, v228
	v_med3_i32 v179, v210, s51, v229
	v_add_u32_e32 v180, 1, v210
	v_lshl_add_u32 v190, v183, 2, s6
	v_med3_i32 v183, v182, s50, v228
	v_med3_i32 v182, v182, s51, v229
	v_lshl_add_u32 v178, v178, 2, s6
	v_lshl_add_u32 v179, v179, 2, s6
	v_med3_i32 v181, v180, s50, v228
	v_med3_i32 v180, v180, s51, v229
	v_lshl_add_u32 v191, v183, 2, s6
	v_lshl_add_u32 v193, v182, 2, s6
	v_lshl_add_u32 v181, v181, 2, s6
	v_lshl_add_u32 v180, v180, 2, s6
	ds_read_b32 v178, v178 offset:512
	ds_read_b32 v182, v179 offset:640
	ds_read_b32 v179, v181 offset:512
	ds_read_b32 v183, v180 offset:640
	ds_read_b32 v190, v190 offset:512
	ds_read_b32 v191, v191 offset:512
	ds_read_b32 v193, v193 offset:640
	ds_read_b32 v192, v192 offset:640
	s_waitcnt lgkmcnt(5)
	v_pk_add_f32 v[180:181], v[128:129], v[178:179]
	s_waitcnt lgkmcnt(4)
	v_pk_add_f32 v[178:179], v[144:145], v[182:183]
	s_waitcnt lgkmcnt(2)
	v_pk_add_f32 v[182:183], v[130:131], v[190:191]
	v_add_u32_e32 v190, 8, v210
	v_med3_i32 v191, v190, s50, v228
	v_med3_i32 v190, v190, s51, v229
	v_lshl_add_u32 v194, v190, 2, s6
	v_add_u32_e32 v190, 9, v210
	v_med3_i32 v195, v190, s50, v228
	v_med3_i32 v190, v190, s51, v229
	v_lshl_add_u32 v196, v190, 2, s6
	v_add_u32_e32 v190, 10, v210
	v_med3_i32 v197, v190, s50, v228
	v_med3_i32 v190, v190, s51, v229
	v_lshl_add_u32 v198, v190, 2, s6
	v_add_u32_e32 v190, 11, v210
	v_lshl_add_u32 v191, v191, 2, s6
	v_lshl_add_u32 v195, v195, 2, s6
	v_lshl_add_u32 v197, v197, 2, s6
	v_med3_i32 v199, v190, s50, v228
	v_med3_i32 v190, v190, s51, v229
	v_lshl_add_u32 v199, v199, 2, s6
	v_lshl_add_u32 v200, v190, 2, s6
	ds_read_b32 v190, v191 offset:512
	ds_read_b32 v194, v194 offset:640
	ds_read_b32 v191, v195 offset:512
	ds_read_b32 v195, v196 offset:640
	ds_read_b32 v196, v197 offset:512
	ds_read_b32 v202, v198 offset:640
	ds_read_b32 v197, v199 offset:512
	ds_read_b32 v203, v200 offset:640
	s_waitcnt lgkmcnt(5)
	v_pk_add_f32 v[198:199], v[132:133], v[190:191]
	v_add_u32_e32 v190, 16, v210
	v_med3_i32 v191, v190, s50, v228
	v_med3_i32 v190, v190, s51, v229
	s_waitcnt lgkmcnt(1)
	v_pk_add_f32 v[200:201], v[134:135], v[196:197]
	s_waitcnt lgkmcnt(0)
	v_pk_add_f32 v[196:197], v[150:151], v[202:203]
	v_lshl_add_u32 v202, v190, 2, s6
	v_add_u32_e32 v190, 17, v210
	v_med3_i32 v203, v190, s50, v228
	v_med3_i32 v190, v190, s51, v229
	v_lshl_add_u32 v204, v190, 2, s6
	v_add_u32_e32 v190, 18, v210
	v_med3_i32 v205, v190, s50, v228
	v_med3_i32 v190, v190, s51, v229
	v_lshl_add_u32 v208, v190, 2, s6
	v_add_u32_e32 v190, 19, v210
	v_med3_i32 v206, v190, s50, v228
	v_med3_i32 v190, v190, s51, v229
	v_lshl_add_u32 v191, v191, 2, s6
	v_lshl_add_u32 v203, v203, 2, s6
	v_lshl_add_u32 v207, v206, 2, s6
	v_lshl_add_u32 v209, v190, 2, s6
	v_lshl_add_u32 v205, v205, 2, s6
	ds_read_b32 v190, v191 offset:512
	ds_read_b32 v202, v202 offset:640
	ds_read_b32 v191, v203 offset:512
	ds_read_b32 v203, v204 offset:640
	ds_read_b32 v206, v205 offset:512
	ds_read_b32 v207, v207 offset:512
	ds_read_b32 v209, v209 offset:640
	ds_read_b32 v208, v208 offset:640
	s_waitcnt lgkmcnt(5)
	v_pk_add_f32 v[204:205], v[136:137], v[190:191]
	v_add_u32_e32 v190, 24, v210
	v_med3_i32 v191, v190, s50, v228
	v_med3_i32 v190, v190, s51, v229
	v_lshl_add_u32 v211, v190, 2, s6
	v_add_u32_e32 v190, 25, v210
	v_med3_i32 v212, v190, s50, v228
	v_med3_i32 v190, v190, s51, v229
	v_lshl_add_u32 v213, v190, 2, s6
	v_add_u32_e32 v190, 26, v210
	v_med3_i32 v214, v190, s50, v228
	v_med3_i32 v190, v190, s51, v229
	v_lshl_add_u32 v215, v190, 2, s6
	v_add_u32_e32 v190, 27, v210
	v_lshl_add_u32 v191, v191, 2, s6
	v_lshl_add_u32 v212, v212, 2, s6
	v_med3_i32 v210, v190, s50, v228
	v_med3_i32 v190, v190, s51, v229
	v_lshl_add_u32 v214, v214, 2, s6
	v_lshl_add_u32 v216, v210, 2, s6
	v_lshl_add_u32 v217, v190, 2, s6
	ds_read_b32 v190, v191 offset:512
	ds_read_b32 v210, v211 offset:640
	ds_read_b32 v191, v212 offset:512
	ds_read_b32 v211, v213 offset:640
	ds_read_b32 v212, v214 offset:512
	ds_read_b32 v222, v215 offset:640
	ds_read_b32 v213, v216 offset:512
	ds_read_b32 v223, v217 offset:640
	s_waitcnt lgkmcnt(5)
	v_pk_add_f32 v[214:215], v[140:141], v[190:191]
	v_max_f32_e32 v190, v180, v181
	v_max3_f32 v190, v190, v182, v183
	v_max3_f32 v190, v190, v198, v199
	v_max3_f32 v190, v190, v200, v201
	v_pk_add_f32 v[206:207], v[138:139], v[206:207]
	v_max3_f32 v190, v190, v204, v205
	v_max3_f32 v190, v190, v206, v207
	s_waitcnt lgkmcnt(1)
	v_pk_add_f32 v[216:217], v[142:143], v[212:213]
	v_max3_f32 v190, v190, v214, v215
	v_max3_f32 v190, v190, v216, v217
	v_pk_add_f32 v[192:193], v[146:147], v[192:193]
	v_max3_f32 v190, v190, v178, v179
	v_pk_add_f32 v[194:195], v[148:149], v[194:195]
	v_max3_f32 v190, v190, v192, v193
	v_max3_f32 v190, v190, v194, v195
	v_pk_add_f32 v[202:203], v[152:153], v[202:203]
	v_max3_f32 v190, v190, v196, v197
	v_pk_add_f32 v[208:209], v[154:155], v[208:209]
	v_max3_f32 v190, v190, v202, v203
	v_pk_add_f32 v[210:211], v[156:157], v[210:211]
	v_max3_f32 v190, v190, v208, v209
	s_waitcnt lgkmcnt(0)
	v_pk_add_f32 v[212:213], v[158:159], v[222:223]
	v_max3_f32 v190, v190, v210, v211
	v_max3_f32 v190, v190, v212, v213
	v_mov_b32_e32 v191, v190
	s_nop 1
	v_permlane32_swap_b32_e32 v190, v191
	v_max_f32_e32 v191, v191, v191
	v_max_f32_e32 v190, v190, v190
	v_max_f32_e32 v190, v190, v191
	v_add_f32_e32 v221, 0, v190
	v_sub_f32_e32 v190, v221, v249
	v_cmp_ge_f32_e32 vcc, s94, v190
	s_cmp_eq_u64 vcc, exec
	s_mov_b64 s[8:9], 0
	s_cselect_b64 s[6:7], -1, 0

; #define SBAR() __builtin_amdgcn_sched_barrier(0)
; template <int OFF> __device__ __forceinline__ s16x4 tr_read(unsigned vb) { s16x4 r; asm volatile("ds_read_b64_tr_b16 %0, %1 offset:%2" : "=&v"(r) : "v"(vb), "i"(OFF) : "memory"); return r; }
; template <int D0> __device__ __forceinline__ void pv_one(f32x16& od, unsigned vb, bf16x8 pa0, bf16x8 pa1, bf16x8 pa2, bf16x8 pa3) {
;   const s16x4 l0 = tr_read<v_rd_off(D0, 0, 0)>(vb), h0 = tr_read<v_rd_off(D0, 0, 1)>(vb), l1 = tr_read<v_rd_off(D0, 1, 0)>(vb), h1 = tr_read<v_rd_off(D0, 1, 1)>(vb);
;   const s16x4 l2 = tr_read<v_rd_off(D0, 2, 0)>(vb), h2 = tr_read<v_rd_off(D0, 2, 1)>(vb), l3 = tr_read<v_rd_off(D0, 3, 0)>(vb), h3 = tr_read<v_rd_off(D0, 3, 1)>(vb);
;   asm volatile("s_waitcnt lgkmcnt(0)" ::: "memory"); SBAR();
;     ...
;   od = __builtin_amdgcn_mfma_f32_32x32x16_bf16(pa0, PK(l0, h0), od, 0, 0, 0);
;   od = __builtin_amdgcn_mfma_f32_32x32x16_bf16(pa1, PK(l1, h1), od, 0, 0, 0);
;   od = __builtin_amdgcn_mfma_f32_32x32x16_bf16(pa2, PK(l2, h2), od, 0, 0, 0);
;   od = __builtin_amdgcn_mfma_f32_32x32x16_bf16(pa3, PK(l3, h3), od, 0, 0, 0);
;     ...
; }
; __device__ __forceinline__ void finishSM(f32x16& p0, f32x16& p1, float alpha, float& l_reg, bf16x8& pa0, bf16x8& pa1, bf16x8& pa2, bf16x8& pa3) {
; #pragma unroll
;   for (int r = 0; r < 16; ++r) p1[r] = __builtin_amdgcn_exp2f(p1[r]);
;   float ps = 0;
; #pragma unroll
;   for (int r = 0; r < 16; ++r) ps += p0[r];
; #pragma unroll
;   for (int r = 0; r < 16; ++r) ps += p1[r];
;   { auto rr = __builtin_amdgcn_permlane32_swap(__float_as_uint(ps), __float_as_uint(ps), false, false);
;     ps = __uint_as_float(rr[0]) + __uint_as_float(rr[1]); }
;   l_reg = l_reg * alpha + ps;
;     ...
;   PK4(p0, 0, pa0); PK4(p0, 8, pa1); PK4(p1, 0, pa2); PK4(p1, 8, pa3);
;     ...
; }
.Ljoin_p2:
	v_exp_f32_e32 v132, v132
	v_exp_f32_e32 v133, v133
	v_exp_f32_e32 v181, v128
	v_add_f32_e32 v128, 0, v129
	v_exp_f32_e32 v134, v134
	v_add_f32_e32 v128, v130, v128
	v_exp_f32_e32 v135, v135
	v_add_f32_e32 v128, v131, v128
	v_exp_f32_e32 v136, v136
	v_add_f32_e32 v128, v132, v128
	v_exp_f32_e32 v137, v137
	v_add_f32_e32 v128, v133, v128
	v_exp_f32_e32 v138, v138
	v_add_f32_e32 v128, v134, v128
	v_exp_f32_e32 v139, v139
	v_add_f32_e32 v128, v135, v128
	v_exp_f32_e32 v140, v140
	v_add_f32_e32 v128, v136, v128
	v_exp_f32_e32 v141, v141
	v_add_f32_e32 v128, v137, v128
	v_exp_f32_e32 v142, v142
	v_add_f32_e32 v128, v138, v128
	v_exp_f32_e32 v143, v143
	v_add_f32_e32 v128, v139, v128
	v_exp_f32_e32 v179, v145
	v_add_f32_e32 v128, v140, v128
	v_exp_f32_e32 v180, v146
	v_add_f32_e32 v128, v141, v128
	v_exp_f32_e32 v147, v147
	v_add_f32_e32 v128, v142, v128
	v_exp_f32_e32 v148, v148
	v_add_f32_e32 v128, v143, v128
	v_exp_f32_e32 v149, v149
	v_add_f32_e32 v128, v179, v128
	v_exp_f32_e32 v150, v150
	v_add_f32_e32 v128, v180, v128
	v_exp_f32_e32 v151, v151
	v_add_f32_e32 v128, v147, v128
	v_exp_f32_e32 v152, v152
	v_add_f32_e32 v128, v148, v128
	v_exp_f32_e32 v153, v153
	v_add_f32_e32 v128, v149, v128
	v_exp_f32_e32 v154, v154
	v_add_f32_e32 v128, v150, v128
	v_exp_f32_e32 v155, v155
	v_add_f32_e32 v128, v151, v128
	v_exp_f32_e32 v156, v156
	v_add_f32_e32 v128, v152, v128
	v_exp_f32_e32 v157, v157
	v_add_f32_e32 v128, v153, v128
	v_exp_f32_e32 v158, v158
	v_add_f32_e32 v128, v154, v128
	v_exp_f32_e32 v159, v159
	v_add_f32_e32 v128, v155, v128
	v_exp_f32_e32 v178, v178
	v_add_f32_e32 v128, v156, v128
	v_add_f32_e32 v128, v157, v128
	v_add_f32_e32 v128, v158, v128
	v_add_f32_e32 v128, v159, v128
	v_add_f32_e32 v128, v178, v128
	v_add_f32_e32 v145, v181, v128
	v_mov_b32_e32 v146, v145
	s_nop 1
	v_permlane32_swap_b32_e32 v145, v146
	v_cvt_pk_bf16_f32 v128, v129, v130
	v_cvt_pk_bf16_f32 v129, v131, v132
	v_cvt_pk_bf16_f32 v130, v133, v134
	v_cvt_pk_bf16_f32 v131, v135, v136
	v_cvt_pk_bf16_f32 v132, v137, v138
	v_cvt_pk_bf16_f32 v133, v139, v140
	v_cvt_pk_bf16_f32 v134, v141, v142
	v_cvt_pk_bf16_f32 v135, v143, v179
	v_cvt_pk_bf16_f32 v136, v180, v147
	v_cvt_pk_bf16_f32 v137, v148, v149
	v_cvt_pk_bf16_f32 v138, v150, v151
	v_cvt_pk_bf16_f32 v139, v152, v153
	v_cvt_pk_bf16_f32 v140, v154, v155
	v_cvt_pk_bf16_f32 v141, v156, v157
	v_cvt_pk_bf16_f32 v142, v158, v159
	v_cvt_pk_bf16_f32 v143, v178, v181
	v_permlane32_swap_b32_e32 v128, v130
	v_permlane32_swap_b32_e32 v129, v131
	v_permlane32_swap_b32_e32 v132, v134
	v_permlane32_swap_b32_e32 v133, v135
	v_permlane32_swap_b32_e32 v136, v138
	v_permlane32_swap_b32_e32 v137, v139
	v_permlane32_swap_b32_e32 v140, v142
	v_permlane32_swap_b32_e32 v141, v143
	s_lshl_b32 s6, s19, 15
	v_add_u32_e32 v147, s6, v247
	ds_read_b64_tr_b16 v[148:149], v147 offset:0
	ds_read_b64_tr_b16 v[150:151], v147 offset:0x800
	ds_read_b64_tr_b16 v[152:153], v147 offset:0x1000
	ds_read_b64_tr_b16 v[154:155], v147 offset:0x1800
	ds_read_b64_tr_b16 v[156:157], v147 offset:0x2000
	ds_read_b64_tr_b16 v[158:159], v147 offset:0x2800
	ds_read_b64_tr_b16 v[178:179], v147 offset:0x3000
	ds_read_b64_tr_b16 v[180:181], v147 offset:0x3800
	s_waitcnt lgkmcnt(6)
	s_nop 0
	v_mfma_f32_32x32x16_bf16 v[48:63], v[128:131], v[148:151], v[48:63]
	ds_read_b64_tr_b16 v[148:149], v147 offset:0x200
	ds_read_b64_tr_b16 v[150:151], v147 offset:0xa00
	s_waitcnt lgkmcnt(6)
	v_mfma_f32_32x32x16_bf16 v[48:63], v[132:135], v[152:155], v[48:63]
	ds_read_b64_tr_b16 v[152:153], v147 offset:0x1200
	ds_read_b64_tr_b16 v[154:155], v147 offset:0x1a00
	s_waitcnt lgkmcnt(6)
	v_mfma_f32_32x32x16_bf16 v[48:63], v[136:139], v[156:159], v[48:63]
	ds_read_b64_tr_b16 v[156:157], v147 offset:0x2200
	ds_read_b64_tr_b16 v[158:159], v147 offset:0x2a00
	s_waitcnt lgkmcnt(6)
	v_mfma_f32_32x32x16_bf16 v[48:63], v[140:143], v[178:181], v[48:63]
	ds_read_b64_tr_b16 v[178:179], v147 offset:0x3200
	ds_read_b64_tr_b16 v[180:181], v147 offset:0x3a00
	s_waitcnt lgkmcnt(6)
	v_mfma_f32_32x32x16_bf16 v[32:47], v[128:131], v[148:151], v[32:47]
	ds_read_b64_tr_b16 v[148:149], v147 offset:0x400
	ds_read_b64_tr_b16 v[150:151], v147 offset:0xc00
	s_waitcnt lgkmcnt(6)
	v_mfma_f32_32x32x16_bf16 v[32:47], v[132:135], v[152:155], v[32:47]
	ds_read_b64_tr_b16 v[152:153], v147 offset:0x1400
	ds_read_b64_tr_b16 v[154:155], v147 offset:0x1c00
	s_waitcnt lgkmcnt(6)
	v_mfma_f32_32x32x16_bf16 v[32:47], v[136:139], v[156:159], v[32:47]
	ds_read_b64_tr_b16 v[156:157], v147 offset:0x2400
	ds_read_b64_tr_b16 v[158:159], v147 offset:0x2c00
	s_waitcnt lgkmcnt(6)
	v_mfma_f32_32x32x16_bf16 v[32:47], v[140:143], v[178:181], v[32:47]
	ds_read_b64_tr_b16 v[178:179], v147 offset:0x3400
	ds_read_b64_tr_b16 v[180:181], v147 offset:0x3c00
	s_waitcnt lgkmcnt(6)
	v_mfma_f32_32x32x16_bf16 v[0:15], v[128:131], v[148:151], v[0:15]
	ds_read_b64_tr_b16 v[148:149], v147 offset:0x600
	ds_read_b64_tr_b16 v[150:151], v147 offset:0xe00
	s_waitcnt lgkmcnt(6)
; #define BARL() asm volatile("s_waitcnt lgkmcnt(0)\n\ts_barrier" ::: "memory")
; #define BARL() asm volatile("s_waitcnt lgkmcnt(0)\n\ts_barrier" ::: "memory")
; __device__ __forceinline__ void attn_pass_dv256(const bf16_t* __restrict__ Qb, const bf16_t* __restrict__ Kh, const bf16_t* __restrict__ Vh, int qpos0,
;                                                 LAS unsigned char* lds, f32x16 (&o)[8], float& l_out, int wave_) {
;     ...
;     pv_one<0>(o[0], vbs, pa0, pa1, pa2, pa3); pv_one<1>(o[1], vbs, pa0, pa1, pa2, pa3); pv_one<2>(o[2], vbs, pa0, pa1, pa2, pa3); pv_one<3>(o[3], vbs, pa0, pa1, pa2, pa3);
;     pv_one<0>(o[4], vbs + 16384, pa0, pa1, pa2, pa3); pv_one<1>(o[5], vbs + 16384, pa0, pa1, pa2, pa3); pv_one<2>(o[6], vbs + 16384, pa0, pa1, pa2, pa3); pv_one<3>(o[7], vbs + 16384, pa0, pa1, pa2, pa3);
;     asm volatile("s_waitcnt vmcnt(0)" ::: "memory"); BARL();
;     if (j + 2 < NT) DMA_KV(j + 2, sl);
	v_mfma_f32_32x32x16_bf16 v[0:15], v[132:135], v[152:155], v[0:15]
	ds_read_b64_tr_b16 v[152:153], v147 offset:0x1600
	ds_read_b64_tr_b16 v[154:155], v147 offset:0x1e00
	s_waitcnt lgkmcnt(6)
	v_mfma_f32_32x32x16_bf16 v[0:15], v[136:139], v[156:159], v[0:15]
	ds_read_b64_tr_b16 v[156:157], v147 offset:0x2600
	ds_read_b64_tr_b16 v[158:159], v147 offset:0x2e00
	s_waitcnt lgkmcnt(6)
	v_mfma_f32_32x32x16_bf16 v[0:15], v[140:143], v[178:181], v[0:15]
	ds_read_b64_tr_b16 v[178:179], v147 offset:0x3600
	ds_read_b64_tr_b16 v[180:181], v147 offset:0x3e00
	s_waitcnt lgkmcnt(6)
	v_mfma_f32_32x32x16_bf16 v[16:31], v[128:131], v[148:151], v[16:31]
	v_add_u32_e32 v147, 0x4000, v147
	ds_read_b64_tr_b16 v[148:149], v147 offset:0
	ds_read_b64_tr_b16 v[150:151], v147 offset:0x800
	s_waitcnt lgkmcnt(6)
	v_mfma_f32_32x32x16_bf16 v[16:31], v[132:135], v[152:155], v[16:31]
	ds_read_b64_tr_b16 v[152:153], v147 offset:0x1000
	ds_read_b64_tr_b16 v[154:155], v147 offset:0x1800
	s_waitcnt lgkmcnt(6)
	v_mfma_f32_32x32x16_bf16 v[16:31], v[136:139], v[156:159], v[16:31]
	ds_read_b64_tr_b16 v[156:157], v147 offset:0x2000
	ds_read_b64_tr_b16 v[158:159], v147 offset:0x2800
	s_waitcnt lgkmcnt(6)
	v_mfma_f32_32x32x16_bf16 v[16:31], v[140:143], v[178:181], v[16:31]
	ds_read_b64_tr_b16 v[178:179], v147 offset:0x3000
	ds_read_b64_tr_b16 v[180:181], v147 offset:0x3800
	s_waitcnt lgkmcnt(6)
	v_mfma_f32_32x32x16_bf16 v[64:79], v[128:131], v[148:151], v[64:79]
	ds_read_b64_tr_b16 v[148:149], v147 offset:0x200
	ds_read_b64_tr_b16 v[150:151], v147 offset:0xa00
	s_waitcnt lgkmcnt(6)
	v_mfma_f32_32x32x16_bf16 v[64:79], v[132:135], v[152:155], v[64:79]
	ds_read_b64_tr_b16 v[152:153], v147 offset:0x1200
	ds_read_b64_tr_b16 v[154:155], v147 offset:0x1a00
	s_waitcnt lgkmcnt(6)
	v_mfma_f32_32x32x16_bf16 v[64:79], v[136:139], v[156:159], v[64:79]
	ds_read_b64_tr_b16 v[156:157], v147 offset:0x2200
	ds_read_b64_tr_b16 v[158:159], v147 offset:0x2a00
	s_waitcnt lgkmcnt(6)
	v_mfma_f32_32x32x16_bf16 v[64:79], v[140:143], v[178:181], v[64:79]
	ds_read_b64_tr_b16 v[178:179], v147 offset:0x3200
	ds_read_b64_tr_b16 v[180:181], v147 offset:0x3a00
	s_waitcnt lgkmcnt(6)
	v_mfma_f32_32x32x16_bf16 v[80:95], v[128:131], v[148:151], v[80:95]
	ds_read_b64_tr_b16 v[148:149], v147 offset:0x400
	ds_read_b64_tr_b16 v[150:151], v147 offset:0xc00
	s_waitcnt lgkmcnt(6)
	v_mfma_f32_32x32x16_bf16 v[80:95], v[132:135], v[152:155], v[80:95]
	ds_read_b64_tr_b16 v[152:153], v147 offset:0x1400
	ds_read_b64_tr_b16 v[154:155], v147 offset:0x1c00
	s_waitcnt lgkmcnt(6)
	v_mfma_f32_32x32x16_bf16 v[80:95], v[136:139], v[156:159], v[80:95]
	ds_read_b64_tr_b16 v[156:157], v147 offset:0x2400
	ds_read_b64_tr_b16 v[158:159], v147 offset:0x2c00
	s_waitcnt lgkmcnt(6)
	v_mfma_f32_32x32x16_bf16 v[80:95], v[140:143], v[178:181], v[80:95]
	ds_read_b64_tr_b16 v[178:179], v147 offset:0x3400
	ds_read_b64_tr_b16 v[180:181], v147 offset:0x3c00
	s_waitcnt lgkmcnt(6)
	v_mfma_f32_32x32x16_bf16 v[96:111], v[128:131], v[148:151], v[96:111]
	ds_read_b64_tr_b16 v[148:149], v147 offset:0x600
	ds_read_b64_tr_b16 v[150:151], v147 offset:0xe00
	s_waitcnt lgkmcnt(6)
	v_mfma_f32_32x32x16_bf16 v[96:111], v[132:135], v[152:155], v[96:111]
	ds_read_b64_tr_b16 v[152:153], v147 offset:0x1600
	ds_read_b64_tr_b16 v[154:155], v147 offset:0x1e00
	s_waitcnt lgkmcnt(6)
	v_mfma_f32_32x32x16_bf16 v[96:111], v[136:139], v[156:159], v[96:111]
	ds_read_b64_tr_b16 v[156:157], v147 offset:0x2600
	ds_read_b64_tr_b16 v[158:159], v147 offset:0x2e00
	s_waitcnt lgkmcnt(6)
	v_mfma_f32_32x32x16_bf16 v[96:111], v[140:143], v[178:181], v[96:111]
	ds_read_b64_tr_b16 v[178:179], v147 offset:0x3600
	ds_read_b64_tr_b16 v[180:181], v147 offset:0x3e00
	s_waitcnt lgkmcnt(6)
	v_mfma_f32_32x32x16_bf16 v[112:127], v[128:131], v[148:151], v[112:127]
	s_waitcnt vmcnt(0)
	s_waitcnt lgkmcnt(0)
	s_barrier
	s_cmp_gt_u32 s17, 61
	v_mfma_f32_32x32x16_bf16 v[112:127], v[132:135], v[152:155], v[112:127]
	v_mfma_f32_32x32x16_bf16 v[112:127], v[136:139], v[156:159], v[112:127]
	v_mfma_f32_32x32x16_bf16 v[112:127], v[140:143], v[178:181], v[112:127]
	s_cbranch_scc1 .LBB0_399
	s_add_u32 s7, s12, s27
	s_addc_u32 s19, s13, 0
	s_add_u32 s8, s7, 0x21080100
	s_addc_u32 s9, s19, 0
	s_add_u32 s31, s10, s27
	s_addc_u32 s36, s11, 0
	s_add_u32 s24, s31, 0x29080000
	s_addc_u32 s25, s36, 0
	s_add_i32 s18, s18, 0
	s_add_i32 s18, s18, 0x10000
	s_add_i32 s37, s18, s68
	s_mov_b32 m0, s37
	s_nop 0
	global_load_lds_dwordx4 v235, s[8:9]
	s_add_u32 s8, s7, 0x210a0100
	s_addc_u32 s9, s19, 0
	s_add_i32 s18, s18, s0
	s_mov_b32 m0, s18
	s_nop 0
	global_load_lds_dwordx4 v235, s[8:9]
	s_add_i32 s8, s6, 0
	s_add_i32 s6, s8, s68
	s_mov_b32 m0, s6
	s_nop 0
	global_load_lds_dwordx4 v236, s[24:25]
	s_add_u32 s6, s31, 0x290a0000
	s_addc_u32 s7, s36, 0
	s_add_i32 s9, s8, s0
	s_mov_b32 m0, s9
	s_nop 0
	global_load_lds_dwordx4 v236, s[6:7]
	s_add_u32 s6, s31, 0x29080100
	s_addc_u32 s7, s36, 0
	s_addk_i32 s8, 0x4000
	s_add_i32 s9, s8, s68
	s_mov_b32 m0, s9
	s_nop 0
	global_load_lds_dwordx4 v236, s[6:7]
	s_add_u32 s6, s31, 0x290a0100
	s_addc_u32 s7, s36, 0
	s_add_i32 s8, s8, s0
	s_mov_b32 m0, s8
	s_nop 0
	global_load_lds_dwordx4 v236, s[6:7]
